# GU mid stores: nt for row groups 0-1 (read from HBM by Down anyway), plain for groups 2-3 (kept resident for the reversed Down order)
# baseline (speedup 1.0000x reference)
; __device__ __forceinline__ u32x4 pack8(const f32x4 a, const f32x4 b) { u32x4 w; w.x = cvt_pk_rtz(a[0], a[1]); w.y = cvt_pk_rtz(a[2], a[3]); w.z = cvt_pk_rtz(b[0], b[1]); w.w = cvt_pk_rtz(b[2], b[3]); return w; }
; template <class T> __device__ __forceinline__ T* at(const void* base, unsigned byteoff) { return (T*)((char*)base + byteoff); }
;     __device__ __forceinline__ void operator()(const Acc& acc, const pg8::Unit& u, int wr, int wc, int fr, int fq, LAS float* rcache, int& cached_pm) const {
;         const int row0 = u.pm * 256 + wr * 64 + fr, col0 = u.pn * 128 + wc * 32 + 8 * fq;
;         float rs8[8]; get_rstd8(ssq, u.pm, row0, fr, fq, rcache, cached_pm, rs8);
; #pragma unroll
;         for (int ai = 0; ai < 2; ++ai)
; #pragma unroll
;             for (int m = 0; m < 4; ++m) {
;                 const int row = row0 + ai * 128 + m * 16; const float rs = rs8[ai * 4 + m], nrl = rs * -1.4426950408889634f, rs2 = rs * rs;
;                 f32x4 o[2];
; #pragma unroll
;                 for (int n = 0; n < 2; ++n) { const f32x4 gv = acc[ai][0][m][n], uv = acc[ai][1][m][n]; const f32x4 t = gv * nrl; f32x4 e;
; #pragma unroll
;                     for (int j = 0; j < 4; ++j) e[j] = __builtin_amdgcn_exp2f(t[j]);
;                     e = e + 1.0f; f32x4 r;
; #pragma unroll
;                     for (int j = 0; j < 4; ++j) r[j] = __builtin_amdgcn_rcpf(e[j]);
;                     o[n] = ((gv * uv) * rs2) * r; }
;     ...
;                 *at<u32x4>(O, (unsigned)(row * DFF + col0) * 2u) = pack8(o[0], o[1]) & 0xFFF8FFF8u;
;     ...
;                 __builtin_nontemporal_store(pack8(o[0], o[1]), at<u32x4>(O, (unsigned)(row * DFF + col0) * 2u));
.LBB0_94:
	s_waitcnt lgkmcnt(0)
	v_mul_f32_e32 v132, 0xbfb8aa3b, v160
	v_pk_mul_f32 v[134:135], v[124:125], v[132:133] op_sel_hi:[1,0]
	v_pk_mul_f32 v[136:137], v[122:123], v[132:133] op_sel_hi:[1,0]
	v_lshl_or_b32 v133, s67, 7, v171
	v_pk_mul_f32 v[122:123], v[126:127], v[122:123]
	v_pk_mul_f32 v[126:127], v[120:121], v[132:133] op_sel_hi:[1,0]
	v_exp_f32_e32 v136, v136
	v_exp_f32_e32 v126, v126
	v_exp_f32_e32 v127, v127
	v_exp_f32_e32 v134, v134
	v_exp_f32_e32 v135, v135
	v_exp_f32_e32 v137, v137
	v_pk_mul_f32 v[124:125], v[128:129], v[124:125]
	v_pk_mul_f32 v[128:129], v[118:119], v[132:133] op_sel_hi:[1,0]
	v_pk_add_f32 v[126:127], v[126:127], 1.0 op_sel_hi:[1,0]
	v_pk_add_f32 v[134:135], v[134:135], 1.0 op_sel_hi:[1,0]
	v_pk_add_f32 v[136:137], v[136:137], 1.0 op_sel_hi:[1,0]
	v_exp_f32_e32 v128, v128
	v_exp_f32_e32 v129, v129
	v_rcp_f32_e32 v126, v126
	v_rcp_f32_e32 v127, v127
	v_rcp_f32_e32 v136, v136
	v_rcp_f32_e32 v137, v137
	v_rcp_f32_e32 v134, v134
	v_rcp_f32_e32 v135, v135
	v_mul_f32_e32 v140, v160, v160
	v_pk_mul_f32 v[116:117], v[116:117], v[120:121]
	v_pk_mul_f32 v[122:123], v[122:123], v[140:141] op_sel_hi:[1,0]
	v_pk_mul_f32 v[116:117], v[116:117], v[140:141] op_sel_hi:[1,0]
	v_pk_mul_f32 v[124:125], v[124:125], v[140:141] op_sel_hi:[1,0]
	v_pk_add_f32 v[128:129], v[128:129], 1.0 op_sel_hi:[1,0]
	v_pk_mul_f32 v[120:121], v[116:117], v[126:127]
	v_pk_mul_f32 v[124:125], v[124:125], v[134:135]
	v_pk_mul_f32 v[122:123], v[122:123], v[136:137]
	v_rcp_f32_e32 v128, v128
	v_rcp_f32_e32 v129, v129
	v_pk_mul_f32 v[114:115], v[114:115], v[118:119]
	v_cvt_pk_bf16_f32 v119, v120, v121
	v_mul_f32_e32 v120, 0xbfb8aa3b, v161
	v_cvt_pk_bf16_f32 v116, v122, v123
	v_cvt_pk_bf16_f32 v117, v124, v125
	v_pk_mul_f32 v[122:123], v[112:113], v[120:121] op_sel_hi:[1,0]
	v_pk_mul_f32 v[124:125], v[110:111], v[120:121] op_sel_hi:[1,0]
	v_pk_mul_f32 v[108:109], v[108:109], v[112:113]
	v_pk_mul_f32 v[106:107], v[106:107], v[110:111]
	v_pk_mul_f32 v[110:111], v[104:105], v[120:121] op_sel_hi:[1,0]
	v_pk_mul_f32 v[112:113], v[102:103], v[120:121] op_sel_hi:[1,0]
	v_exp_f32_e32 v110, v110
	v_exp_f32_e32 v112, v112
	v_exp_f32_e32 v111, v111
	v_exp_f32_e32 v113, v113
	v_pk_mul_f32 v[114:115], v[114:115], v[140:141] op_sel_hi:[1,0]
	v_exp_f32_e32 v124, v124
	v_exp_f32_e32 v122, v122
	v_exp_f32_e32 v123, v123
	v_exp_f32_e32 v125, v125
	v_pk_mul_f32 v[114:115], v[114:115], v[128:129]
	s_movk_i32 s2, 0xb00
	v_cvt_pk_bf16_f32 v118, v114, v115
	v_mul_lo_u32 v114, v173, s2
	v_add_lshl_u32 v114, v114, v133, 1
	v_pk_add_f32 v[110:111], v[110:111], 1.0 op_sel_hi:[1,0]
	v_pk_add_f32 v[112:113], v[112:113], 1.0 op_sel_hi:[1,0]
	s_bitcmp1_b32 s66, 4
	s_cbranch_scc1 .Lgu_st_plain1
	global_store_dwordx4 v114, v[116:119], s[24:25] nt
	s_branch .Lgu_st_done1
.Lgu_st_plain1:
	global_store_dwordx4 v114, v[116:119], s[24:25]
.Lgu_st_done1:
	v_rcp_f32_e32 v112, v112
	v_rcp_f32_e32 v113, v113
	v_pk_add_f32 v[118:119], v[122:123], 1.0 op_sel_hi:[1,0]
	v_pk_add_f32 v[122:123], v[124:125], 1.0 op_sel_hi:[1,0]
	v_rcp_f32_e32 v110, v110
	v_rcp_f32_e32 v111, v111
	v_rcp_f32_e32 v122, v122
	v_rcp_f32_e32 v123, v123
	v_mul_f32_e32 v116, v161, v161
	v_pk_mul_f32 v[100:101], v[100:101], v[104:105]
	v_pk_mul_f32 v[98:99], v[98:99], v[102:103]
	v_pk_mul_f32 v[100:101], v[100:101], v[116:117] op_sel_hi:[1,0]
	v_pk_mul_f32 v[98:99], v[98:99], v[116:117] op_sel_hi:[1,0]
	v_pk_mul_f32 v[106:107], v[106:107], v[116:117] op_sel_hi:[1,0]
	v_pk_mul_f32 v[102:103], v[100:101], v[110:111]
	v_pk_mul_f32 v[100:101], v[98:99], v[112:113]
	v_pk_mul_f32 v[106:107], v[106:107], v[122:123]
	v_cvt_pk_bf16_f32 v100, v100, v101
	v_cvt_pk_bf16_f32 v101, v102, v103
	v_add_u32_e32 v103, 0x16000, v114
	v_mul_f32_e32 v102, 0xbfb8aa3b, v158
	v_rcp_f32_e32 v118, v118
	v_rcp_f32_e32 v119, v119
	v_cvt_pk_bf16_f32 v98, v106, v107
	v_pk_mul_f32 v[104:105], v[96:97], v[102:103] op_sel_hi:[1,0]
	v_pk_mul_f32 v[106:107], v[94:95], v[102:103] op_sel_hi:[1,0]
	v_pk_mul_f32 v[92:93], v[92:93], v[96:97]
	v_pk_mul_f32 v[90:91], v[90:91], v[94:95]
	v_pk_mul_f32 v[94:95], v[88:89], v[102:103] op_sel_hi:[1,0]
	v_pk_mul_f32 v[96:97], v[86:87], v[102:103] op_sel_hi:[1,0]
	v_exp_f32_e32 v94, v94
	v_exp_f32_e32 v96, v96
	v_exp_f32_e32 v95, v95
	v_exp_f32_e32 v97, v97
	v_exp_f32_e32 v106, v106
	v_exp_f32_e32 v104, v104
	v_exp_f32_e32 v105, v105
	v_exp_f32_e32 v107, v107
	v_pk_mul_f32 v[108:109], v[108:109], v[116:117] op_sel_hi:[1,0]
	v_pk_add_f32 v[94:95], v[94:95], 1.0 op_sel_hi:[1,0]
	v_pk_mul_f32 v[108:109], v[108:109], v[118:119]
	v_pk_add_f32 v[96:97], v[96:97], 1.0 op_sel_hi:[1,0]
	v_cvt_pk_bf16_f32 v99, v108, v109
	s_bitcmp1_b32 s66, 4
	s_cbranch_scc1 .Lgu_st_plain2
	global_store_dwordx4 v103, v[98:101], s[24:25] nt
	s_branch .Lgu_st_done2
.Lgu_st_plain2:
	global_store_dwordx4 v103, v[98:101], s[24:25]
; __device__ __forceinline__ u32x4 pack8(const f32x4 a, const f32x4 b) { u32x4 w; w.x = cvt_pk_rtz(a[0], a[1]); w.y = cvt_pk_rtz(a[2], a[3]); w.z = cvt_pk_rtz(b[0], b[1]); w.w = cvt_pk_rtz(b[2], b[3]); return w; }
; template <class T> __device__ __forceinline__ T* at(const void* base, unsigned byteoff) { return (T*)((char*)base + byteoff); }
;     __device__ __forceinline__ void operator()(const Acc& acc, const pg8::Unit& u, int wr, int wc, int fr, int fq, LAS float* rcache, int& cached_pm) const {
;     ...
;                 const int row = row0 + ai * 128 + m * 16; const float rs = rs8[ai * 4 + m], nrl = rs * -1.4426950408889634f, rs2 = rs * rs;
;                 f32x4 o[2];
; #pragma unroll
;                 for (int n = 0; n < 2; ++n) { const f32x4 gv = acc[ai][0][m][n], uv = acc[ai][1][m][n]; const f32x4 t = gv * nrl; f32x4 e;
; #pragma unroll
;                     for (int j = 0; j < 4; ++j) e[j] = __builtin_amdgcn_exp2f(t[j]);
;                     e = e + 1.0f; f32x4 r;
; #pragma unroll
;                     for (int j = 0; j < 4; ++j) r[j] = __builtin_amdgcn_rcpf(e[j]);
;                     o[n] = ((gv * uv) * rs2) * r; }
;     ...
;                 *at<u32x4>(O, (unsigned)(row * DFF + col0) * 2u) = pack8(o[0], o[1]) & 0xFFF8FFF8u;
;     ...
;                 __builtin_nontemporal_store(pack8(o[0], o[1]), at<u32x4>(O, (unsigned)(row * DFF + col0) * 2u));
.Lgu_st_done2:
	v_rcp_f32_e32 v96, v96
	v_rcp_f32_e32 v97, v97
	v_pk_add_f32 v[100:101], v[104:105], 1.0 op_sel_hi:[1,0]
	v_pk_add_f32 v[104:105], v[106:107], 1.0 op_sel_hi:[1,0]
	v_rcp_f32_e32 v94, v94
	v_rcp_f32_e32 v95, v95
	v_rcp_f32_e32 v104, v104
	v_rcp_f32_e32 v105, v105
	v_mul_f32_e32 v98, v158, v158
	v_pk_mul_f32 v[84:85], v[84:85], v[88:89]
	v_pk_mul_f32 v[82:83], v[82:83], v[86:87]
	v_pk_mul_f32 v[84:85], v[84:85], v[98:99] op_sel_hi:[1,0]
	v_pk_mul_f32 v[82:83], v[82:83], v[98:99] op_sel_hi:[1,0]
	v_pk_mul_f32 v[90:91], v[90:91], v[98:99] op_sel_hi:[1,0]
	v_pk_mul_f32 v[86:87], v[84:85], v[94:95]
	v_pk_mul_f32 v[84:85], v[82:83], v[96:97]
	v_pk_mul_f32 v[90:91], v[90:91], v[104:105]
	v_cvt_pk_bf16_f32 v84, v84, v85
	v_cvt_pk_bf16_f32 v85, v86, v87
	v_add_u32_e32 v87, 0x2c000, v114
	v_mul_f32_e32 v86, 0xbfb8aa3b, v159
	v_rcp_f32_e32 v100, v100
	v_rcp_f32_e32 v101, v101
	v_cvt_pk_bf16_f32 v82, v90, v91
	v_pk_mul_f32 v[88:89], v[78:79], v[86:87] op_sel_hi:[1,0]
	v_pk_mul_f32 v[90:91], v[76:77], v[86:87] op_sel_hi:[1,0]
	v_pk_mul_f32 v[74:75], v[74:75], v[78:79]
	v_pk_mul_f32 v[72:73], v[72:73], v[76:77]
	v_pk_mul_f32 v[76:77], v[70:71], v[86:87] op_sel_hi:[1,0]
	v_pk_mul_f32 v[78:79], v[68:69], v[86:87] op_sel_hi:[1,0]
	v_exp_f32_e32 v76, v76
	v_exp_f32_e32 v78, v78
	v_exp_f32_e32 v77, v77
	v_exp_f32_e32 v79, v79
	v_exp_f32_e32 v90, v90
	v_exp_f32_e32 v88, v88
	v_exp_f32_e32 v89, v89
	v_exp_f32_e32 v91, v91
	v_pk_mul_f32 v[92:93], v[92:93], v[98:99] op_sel_hi:[1,0]
	v_pk_add_f32 v[76:77], v[76:77], 1.0 op_sel_hi:[1,0]
	v_pk_mul_f32 v[92:93], v[92:93], v[100:101]
	v_pk_add_f32 v[78:79], v[78:79], 1.0 op_sel_hi:[1,0]
	v_cvt_pk_bf16_f32 v83, v92, v93
	s_bitcmp1_b32 s66, 4
	s_cbranch_scc1 .Lgu_st_plain3
	global_store_dwordx4 v87, v[82:85], s[24:25] nt
	s_branch .Lgu_st_done3
.Lgu_st_plain3:
	global_store_dwordx4 v87, v[82:85], s[24:25]
.Lgu_st_done3:
	v_rcp_f32_e32 v78, v78
	v_rcp_f32_e32 v79, v79
	v_pk_add_f32 v[84:85], v[88:89], 1.0 op_sel_hi:[1,0]
	v_pk_add_f32 v[88:89], v[90:91], 1.0 op_sel_hi:[1,0]
	v_rcp_f32_e32 v76, v76
	v_rcp_f32_e32 v77, v77
	v_rcp_f32_e32 v88, v88
	v_rcp_f32_e32 v89, v89
	v_mul_f32_e32 v82, v159, v159
	v_pk_mul_f32 v[66:67], v[66:67], v[70:71]
	v_pk_mul_f32 v[64:65], v[64:65], v[68:69]
	v_pk_mul_f32 v[66:67], v[66:67], v[82:83] op_sel_hi:[1,0]
	v_pk_mul_f32 v[64:65], v[64:65], v[82:83] op_sel_hi:[1,0]
	v_pk_mul_f32 v[72:73], v[72:73], v[82:83] op_sel_hi:[1,0]
	v_pk_mul_f32 v[68:69], v[66:67], v[76:77]
	v_pk_mul_f32 v[66:67], v[64:65], v[78:79]
	v_pk_mul_f32 v[72:73], v[72:73], v[88:89]
	v_cvt_pk_bf16_f32 v66, v66, v67
	v_cvt_pk_bf16_f32 v67, v68, v69
	v_add_u32_e32 v69, 0x42000, v114
	v_mul_f32_e32 v68, 0xbfb8aa3b, v138
	v_rcp_f32_e32 v84, v84
	v_rcp_f32_e32 v85, v85
	v_cvt_pk_bf16_f32 v64, v72, v73
	v_pk_mul_f32 v[70:71], v[62:63], v[68:69] op_sel_hi:[1,0]
	v_pk_mul_f32 v[72:73], v[60:61], v[68:69] op_sel_hi:[1,0]
	v_pk_mul_f32 v[58:59], v[58:59], v[62:63]
	v_pk_mul_f32 v[56:57], v[56:57], v[60:61]
	v_pk_mul_f32 v[60:61], v[54:55], v[68:69] op_sel_hi:[1,0]
	v_pk_mul_f32 v[62:63], v[52:53], v[68:69] op_sel_hi:[1,0]
	v_exp_f32_e32 v60, v60
	v_exp_f32_e32 v62, v62
	v_exp_f32_e32 v61, v61
	v_exp_f32_e32 v63, v63
	v_exp_f32_e32 v72, v72
	v_exp_f32_e32 v70, v70
	v_exp_f32_e32 v71, v71
	v_exp_f32_e32 v73, v73
	v_pk_mul_f32 v[74:75], v[74:75], v[82:83] op_sel_hi:[1,0]
	v_pk_add_f32 v[60:61], v[60:61], 1.0 op_sel_hi:[1,0]
	v_pk_mul_f32 v[74:75], v[74:75], v[84:85]
	v_pk_add_f32 v[62:63], v[62:63], 1.0 op_sel_hi:[1,0]
	v_cvt_pk_bf16_f32 v65, v74, v75
	s_bitcmp1_b32 s66, 4
	s_cbranch_scc1 .Lgu_st_plain4
	global_store_dwordx4 v69, v[64:67], s[24:25] nt
	s_branch .Lgu_st_done4
.Lgu_st_plain4:
	global_store_dwordx4 v69, v[64:67], s[24:25]
.Lgu_st_done4:
	v_rcp_f32_e32 v62, v62
	v_rcp_f32_e32 v63, v63
	v_pk_add_f32 v[66:67], v[70:71], 1.0 op_sel_hi:[1,0]
	v_pk_add_f32 v[70:71], v[72:73], 1.0 op_sel_hi:[1,0]
	v_rcp_f32_e32 v60, v60
	v_rcp_f32_e32 v61, v61
	v_rcp_f32_e32 v70, v70
	v_rcp_f32_e32 v71, v71
	v_mul_f32_e32 v64, v138, v138
	v_pk_mul_f32 v[50:51], v[50:51], v[54:55]
	v_pk_mul_f32 v[48:49], v[48:49], v[52:53]
	v_pk_mul_f32 v[50:51], v[50:51], v[64:65] op_sel_hi:[1,0]
	v_pk_mul_f32 v[48:49], v[48:49], v[64:65] op_sel_hi:[1,0]
	v_pk_mul_f32 v[56:57], v[56:57], v[64:65] op_sel_hi:[1,0]
	v_pk_mul_f32 v[52:53], v[50:51], v[60:61]
	v_pk_mul_f32 v[50:51], v[48:49], v[62:63]
	v_pk_mul_f32 v[56:57], v[56:57], v[70:71]
	v_cvt_pk_bf16_f32 v50, v50, v51
	v_cvt_pk_bf16_f32 v51, v52, v53
	v_add_u32_e32 v53, 0xb0000, v114
	v_mul_f32_e32 v52, 0xbfb8aa3b, v139
	v_rcp_f32_e32 v66, v66
	v_rcp_f32_e32 v67, v67
	v_cvt_pk_bf16_f32 v48, v56, v57
	v_pk_mul_f32 v[54:55], v[46:47], v[52:53] op_sel_hi:[1,0]
	v_pk_mul_f32 v[56:57], v[44:45], v[52:53] op_sel_hi:[1,0]
	v_pk_mul_f32 v[42:43], v[42:43], v[46:47]
	v_pk_mul_f32 v[40:41], v[40:41], v[44:45]
	v_pk_mul_f32 v[44:45], v[38:39], v[52:53] op_sel_hi:[1,0]
	v_pk_mul_f32 v[46:47], v[36:37], v[52:53] op_sel_hi:[1,0]
	v_exp_f32_e32 v44, v44
	v_exp_f32_e32 v46, v46
	v_exp_f32_e32 v45, v45
	v_exp_f32_e32 v47, v47
	v_exp_f32_e32 v56, v56
	v_exp_f32_e32 v54, v54
	v_exp_f32_e32 v55, v55
	v_exp_f32_e32 v57, v57
	v_pk_mul_f32 v[58:59], v[58:59], v[64:65] op_sel_hi:[1,0]
	v_pk_add_f32 v[44:45], v[44:45], 1.0 op_sel_hi:[1,0]
	v_pk_mul_f32 v[58:59], v[58:59], v[66:67]
	v_pk_add_f32 v[46:47], v[46:47], 1.0 op_sel_hi:[1,0]
	v_cvt_pk_bf16_f32 v49, v58, v59
	s_bitcmp1_b32 s66, 4
	s_cbranch_scc1 .Lgu_st_plain5
	global_store_dwordx4 v53, v[48:51], s[24:25] nt
	s_branch .Lgu_st_done5
; __device__ __forceinline__ u32x4 pack8(const f32x4 a, const f32x4 b) { u32x4 w; w.x = cvt_pk_rtz(a[0], a[1]); w.y = cvt_pk_rtz(a[2], a[3]); w.z = cvt_pk_rtz(b[0], b[1]); w.w = cvt_pk_rtz(b[2], b[3]); return w; }
; #define PG8_BAR __builtin_amdgcn_s_barrier()
; template <class T> __device__ __forceinline__ T* at(const void* base, unsigned byteoff) { return (T*)((char*)base + byteoff); }
; template <class Epi>
; __device__ __forceinline__ void gemm_phase(LAS unsigned char* lds, const Gemm g, const StaticOrder& S, const Epi& E, int tid_) {
;     ...
;         if (wr == 0) PG8_BAR;
;         E(acc, cur, wr, wc, fr, fq, rcache, cached_pm);
;         if (!has_next) break;
; #pragma unroll
;         for (int a = 0; a < 2; ++a)
; #pragma unroll
;             for (int b = 0; b < 2; ++b)
; #pragma unroll
;                 for (int m = 0; m < 4; ++m)
; #pragma unroll
;                     for (int n = 0; n < 2; ++n) acc[a][b][m][n] = (f32x4){0.f, 0.f, 0.f, 0.f};
;         cur = nxt; cA = nA; cB = nB; ++ui;
;         if (wr == 1) PG8_BAR;
;     __device__ __forceinline__ void operator()(const Acc& acc, const pg8::Unit& u, int wr, int wc, int fr, int fq, LAS float* rcache, int& cached_pm) const {
;     ...
;                 const int row = row0 + ai * 128 + m * 16; const float rs = rs8[ai * 4 + m], nrl = rs * -1.4426950408889634f, rs2 = rs * rs;
;                 f32x4 o[2];
; #pragma unroll
;                 for (int n = 0; n < 2; ++n) { const f32x4 gv = acc[ai][0][m][n], uv = acc[ai][1][m][n]; const f32x4 t = gv * nrl; f32x4 e;
; #pragma unroll
;                     for (int j = 0; j < 4; ++j) e[j] = __builtin_amdgcn_exp2f(t[j]);
;                     e = e + 1.0f; f32x4 r;
; #pragma unroll
;                     for (int j = 0; j < 4; ++j) r[j] = __builtin_amdgcn_rcpf(e[j]);
;                     o[n] = ((gv * uv) * rs2) * r; }
;     ...
;                 *at<u32x4>(O, (unsigned)(row * DFF + col0) * 2u) = pack8(o[0], o[1]) & 0xFFF8FFF8u;
;     ...
;                 __builtin_nontemporal_store(pack8(o[0], o[1]), at<u32x4>(O, (unsigned)(row * DFF + col0) * 2u));
.Lgu_st_plain5:
	global_store_dwordx4 v53, v[48:51], s[24:25]
.Lgu_st_done5:
	v_rcp_f32_e32 v46, v46
	v_rcp_f32_e32 v47, v47
	v_pk_add_f32 v[50:51], v[54:55], 1.0 op_sel_hi:[1,0]
	v_pk_add_f32 v[54:55], v[56:57], 1.0 op_sel_hi:[1,0]
	v_rcp_f32_e32 v44, v44
	v_rcp_f32_e32 v45, v45
	v_rcp_f32_e32 v54, v54
	v_rcp_f32_e32 v55, v55
	v_mul_f32_e32 v48, v139, v139
	v_pk_mul_f32 v[34:35], v[34:35], v[38:39]
	v_pk_mul_f32 v[32:33], v[32:33], v[36:37]
	v_pk_mul_f32 v[34:35], v[34:35], v[48:49] op_sel_hi:[1,0]
	v_pk_mul_f32 v[32:33], v[32:33], v[48:49] op_sel_hi:[1,0]
	v_pk_mul_f32 v[40:41], v[40:41], v[48:49] op_sel_hi:[1,0]
	v_pk_mul_f32 v[36:37], v[34:35], v[44:45]
	v_pk_mul_f32 v[34:35], v[32:33], v[46:47]
	v_pk_mul_f32 v[40:41], v[40:41], v[54:55]
	v_cvt_pk_bf16_f32 v34, v34, v35
	v_cvt_pk_bf16_f32 v35, v36, v37
	v_add_u32_e32 v37, 0xc6000, v114
	v_mul_f32_e32 v36, 0xbfb8aa3b, v130
	v_rcp_f32_e32 v50, v50
	v_rcp_f32_e32 v51, v51
	v_cvt_pk_bf16_f32 v32, v40, v41
	v_pk_mul_f32 v[38:39], v[30:31], v[36:37] op_sel_hi:[1,0]
	v_pk_mul_f32 v[40:41], v[28:29], v[36:37] op_sel_hi:[1,0]
	v_pk_mul_f32 v[26:27], v[26:27], v[30:31]
	v_pk_mul_f32 v[24:25], v[24:25], v[28:29]
	v_pk_mul_f32 v[28:29], v[22:23], v[36:37] op_sel_hi:[1,0]
	v_pk_mul_f32 v[30:31], v[20:21], v[36:37] op_sel_hi:[1,0]
	v_exp_f32_e32 v28, v28
	v_exp_f32_e32 v30, v30
	v_exp_f32_e32 v29, v29
	v_exp_f32_e32 v31, v31
	v_exp_f32_e32 v40, v40
	v_exp_f32_e32 v38, v38
	v_exp_f32_e32 v39, v39
	v_exp_f32_e32 v41, v41
	v_pk_mul_f32 v[42:43], v[42:43], v[48:49] op_sel_hi:[1,0]
	v_pk_add_f32 v[28:29], v[28:29], 1.0 op_sel_hi:[1,0]
	v_pk_mul_f32 v[42:43], v[42:43], v[50:51]
	v_pk_add_f32 v[30:31], v[30:31], 1.0 op_sel_hi:[1,0]
	v_cvt_pk_bf16_f32 v33, v42, v43
	s_bitcmp1_b32 s66, 4
	s_cbranch_scc1 .Lgu_st_plain6
	global_store_dwordx4 v37, v[32:35], s[24:25] nt
	s_branch .Lgu_st_done6
.Lgu_st_plain6:
	global_store_dwordx4 v37, v[32:35], s[24:25]
.Lgu_st_done6:
	v_rcp_f32_e32 v30, v30
	v_rcp_f32_e32 v31, v31
	v_pk_add_f32 v[34:35], v[38:39], 1.0 op_sel_hi:[1,0]
	v_pk_add_f32 v[38:39], v[40:41], 1.0 op_sel_hi:[1,0]
	v_rcp_f32_e32 v28, v28
	v_rcp_f32_e32 v29, v29
	v_rcp_f32_e32 v38, v38
	v_rcp_f32_e32 v39, v39
	v_mul_f32_e32 v32, v130, v130
	v_pk_mul_f32 v[18:19], v[18:19], v[22:23]
	v_pk_mul_f32 v[16:17], v[16:17], v[20:21]
	v_pk_mul_f32 v[18:19], v[18:19], v[32:33] op_sel_hi:[1,0]
	v_pk_mul_f32 v[16:17], v[16:17], v[32:33] op_sel_hi:[1,0]
	v_pk_mul_f32 v[24:25], v[24:25], v[32:33] op_sel_hi:[1,0]
	v_pk_mul_f32 v[20:21], v[18:19], v[28:29]
	v_pk_mul_f32 v[18:19], v[16:17], v[30:31]
	v_rcp_f32_e32 v34, v34
	v_rcp_f32_e32 v35, v35
	v_pk_mul_f32 v[24:25], v[24:25], v[38:39]
	v_cvt_pk_bf16_f32 v18, v18, v19
	v_cvt_pk_bf16_f32 v19, v20, v21
	v_add_u32_e32 v21, 0xdc000, v114
	v_mul_f32_e32 v20, 0xbfb8aa3b, v131
	v_cvt_pk_bf16_f32 v16, v24, v25
	v_pk_mul_f32 v[22:23], v[14:15], v[20:21] op_sel_hi:[1,0]
	v_pk_mul_f32 v[24:25], v[12:13], v[20:21] op_sel_hi:[1,0]
	v_pk_mul_f32 v[10:11], v[10:11], v[14:15]
	v_pk_mul_f32 v[8:9], v[8:9], v[12:13]
	v_pk_mul_f32 v[12:13], v[6:7], v[20:21] op_sel_hi:[1,0]
	v_pk_mul_f32 v[14:15], v[4:5], v[20:21] op_sel_hi:[1,0]
	v_exp_f32_e32 v24, v24
	v_exp_f32_e32 v22, v22
	v_exp_f32_e32 v23, v23
	v_exp_f32_e32 v25, v25
	v_exp_f32_e32 v14, v14
	v_exp_f32_e32 v12, v12
	v_exp_f32_e32 v13, v13
	v_exp_f32_e32 v15, v15
	v_pk_mul_f32 v[26:27], v[26:27], v[32:33] op_sel_hi:[1,0]
	v_pk_mul_f32 v[2:3], v[2:3], v[6:7]
	v_pk_mul_f32 v[26:27], v[26:27], v[34:35]
	v_pk_add_f32 v[12:13], v[12:13], 1.0 op_sel_hi:[1,0]
	v_cvt_pk_bf16_f32 v17, v26, v27
	s_bitcmp1_b32 s66, 4
	s_cbranch_scc1 .Lgu_st_plain7
	global_store_dwordx4 v21, v[16:19], s[24:25] nt
	s_branch .Lgu_st_done7
.Lgu_st_plain7:
	global_store_dwordx4 v21, v[16:19], s[24:25]
.Lgu_st_done7:
	v_pk_add_f32 v[14:15], v[14:15], 1.0 op_sel_hi:[1,0]
	v_rcp_f32_e32 v12, v12
	v_pk_add_f32 v[18:19], v[22:23], 1.0 op_sel_hi:[1,0]
	v_pk_add_f32 v[22:23], v[24:25], 1.0 op_sel_hi:[1,0]
	v_rcp_f32_e32 v18, v18
	v_rcp_f32_e32 v22, v22
	v_rcp_f32_e32 v23, v23
	v_rcp_f32_e32 v19, v19
	v_rcp_f32_e32 v14, v14
	v_rcp_f32_e32 v15, v15
	v_rcp_f32_e32 v13, v13
	v_mul_f32_e32 v16, v131, v131
	v_pk_mul_f32 v[0:1], v[0:1], v[4:5]
	v_pk_mul_f32 v[8:9], v[8:9], v[16:17] op_sel_hi:[1,0]
	v_pk_mul_f32 v[10:11], v[10:11], v[16:17] op_sel_hi:[1,0]
	v_pk_mul_f32 v[0:1], v[0:1], v[16:17] op_sel_hi:[1,0]
	v_pk_mul_f32 v[2:3], v[2:3], v[16:17] op_sel_hi:[1,0]
	v_pk_mul_f32 v[10:11], v[10:11], v[18:19]
	v_pk_mul_f32 v[8:9], v[8:9], v[22:23]
	v_pk_mul_f32 v[4:5], v[2:3], v[12:13]
	v_pk_mul_f32 v[2:3], v[0:1], v[14:15]
	v_cvt_pk_bf16_f32 v0, v8, v9
	v_cvt_pk_bf16_f32 v1, v10, v11
	v_cvt_pk_bf16_f32 v2, v2, v3
	v_cvt_pk_bf16_f32 v3, v4, v5
	v_add_u32_e32 v4, 0xf2000, v114
	s_andn2_b64 vcc, exec, s[38:39]
	s_mov_b64 s[28:29], -1
	s_bitcmp1_b32 s66, 4
	s_cbranch_scc1 .Lgu_st_plain8
	global_store_dwordx4 v4, v[0:3], s[24:25] nt
	s_branch .Lgu_st_done8
.Lgu_st_plain8:
	global_store_dwordx4 v4, v[0:3], s[24:25]
.Lgu_st_done8:
	s_cbranch_vccnz .LBB0_80
	s_andn2_b64 vcc, exec, s[44:45]
	s_cbranch_vccnz .LBB0_79
	s_barrier
	s_branch .LBB0_79
